# v19 + nt hint on the f32 residual-stream / output stores of the LayerNorm phases
# speedup vs baseline: 1.0059x; 1.0059x over previous
.LBB0_521:
	v_lshl_add_u64 v[46:47], s[84:85], 0, v[8:9]
	v_lshl_add_u64 v[10:11], s[16:17], 0, v[6:7]
	v_lshl_add_u64 v[48:49], s[84:85], 0, v[6:7]
	v_add_co_u32_e32 v46, vcc, 0x14400000, v46
	global_load_dwordx4 v[22:25], v[0:1], off
	global_load_dwordx4 v[26:29], v[2:3], off
	global_load_dwordx4 v[30:33], v[10:11], off nt
	global_load_dwordx4 v[34:37], v[10:11], off offset:1024 nt
	global_load_dwordx4 v[38:41], v[10:11], off offset:2048 nt
	global_load_dwordx4 v[42:45], v[10:11], off offset:3072 nt
	v_add_co_u32_e64 v10, s[0:1], s11, v48
	v_addc_co_u32_e32 v47, vcc, 0, v47, vcc
	s_nop 0
	v_addc_co_u32_e64 v11, s[0:1], 0, v49, s[0:1]
	global_load_dwordx2 v[48:49], v[46:47], off nt
	global_load_dwordx2 v[50:51], v[46:47], off offset:512 nt
	global_load_dwordx2 v[52:53], v[46:47], off offset:1024 nt
	s_nop 0
	global_load_dwordx2 v[46:47], v[46:47], off offset:1536 nt
	s_add_i32 s14, s14, s80
	v_lshl_add_u64 v[6:7], v[6:7], 0, s[6:7]
	v_lshl_add_u64 v[8:9], v[8:9], 0, s[8:9]
	s_cmpk_lt_i32 s14, 0x4000
	s_waitcnt vmcnt(3)
	v_lshlrev_b32_e32 v54, 16, v48
	v_and_b32_e32 v55, 0xffff0000, v48
	v_lshlrev_b32_e32 v48, 16, v49
	v_and_b32_e32 v49, 0xffff0000, v49
	s_waitcnt vmcnt(2)
	v_lshlrev_b32_e32 v56, 16, v50
	v_and_b32_e32 v57, 0xffff0000, v50
	v_lshlrev_b32_e32 v50, 16, v51
	v_and_b32_e32 v51, 0xffff0000, v51
	s_waitcnt vmcnt(1)
	v_lshlrev_b32_e32 v58, 16, v52
	v_and_b32_e32 v59, 0xffff0000, v52
	v_lshlrev_b32_e32 v52, 16, v53
	v_and_b32_e32 v53, 0xffff0000, v53
	s_waitcnt vmcnt(0)
	v_lshlrev_b32_e32 v60, 16, v46
	v_and_b32_e32 v61, 0xffff0000, v46
	v_lshlrev_b32_e32 v46, 16, v47
	v_and_b32_e32 v47, 0xffff0000, v47
	v_pk_fma_f32 v[32:33], v[32:33], s[10:11], v[48:49] op_sel_hi:[1,0,1]
	v_pk_fma_f32 v[30:31], v[30:31], s[10:11], v[54:55] op_sel_hi:[1,0,1]
	v_pk_fma_f32 v[36:37], v[36:37], s[10:11], v[50:51] op_sel_hi:[1,0,1]
	v_pk_fma_f32 v[34:35], v[34:35], s[10:11], v[56:57] op_sel_hi:[1,0,1]
	v_pk_fma_f32 v[40:41], v[40:41], s[10:11], v[52:53] op_sel_hi:[1,0,1]
	v_pk_fma_f32 v[44:45], v[44:45], s[10:11], v[46:47] op_sel_hi:[1,0,1]
	v_pk_mov_b32 v[46:47], v[30:31], v[32:33] op_sel:[1,0]
	v_mov_b32_e32 v48, v30
	v_mov_b32_e32 v49, v33
	v_pk_mov_b32 v[50:51], v[34:35], v[36:37] op_sel:[1,0]
	v_mov_b32_e32 v52, v34
	v_mov_b32_e32 v53, v37
	v_pk_add_f32 v[46:47], v[46:47], v[48:49]
	v_pk_add_f32 v[48:49], v[50:51], v[52:53]
	v_pk_fma_f32 v[38:39], v[38:39], s[10:11], v[58:59] op_sel_hi:[1,0,1]
	v_pk_fma_f32 v[42:43], v[42:43], s[10:11], v[60:61] op_sel_hi:[1,0,1]
	v_add_f32_e32 v21, v46, v47
	v_pk_add_f32 v[46:47], v[48:49], v[48:49] op_sel:[0,1] op_sel_hi:[1,0]
	v_add_f32_e32 v54, v38, v39
	v_add_f32_e32 v56, v40, v41
	v_mov_b32_e32 v59, v42
	v_mov_b32_e32 v55, v44
	v_mov_b32_e32 v57, v45
	v_add_f32_e32 v58, 0, v21
	v_mov_b32_e32 v47, v43
	v_pk_add_f32 v[50:51], v[54:55], v[56:57]
	v_pk_add_f32 v[46:47], v[58:59], v[46:47]
	s_nop 0
	v_pk_add_f32 v[46:47], v[46:47], v[50:51]
	s_nop 0
	v_add_f32_e32 v21, v46, v47
	ds_bpermute_b32 v46, v12, v21
	s_waitcnt lgkmcnt(0)
	v_add_f32_e32 v21, v21, v46
	ds_bpermute_b32 v46, v13, v21
	s_waitcnt lgkmcnt(0)
	v_add_f32_e32 v21, v21, v46
	ds_bpermute_b32 v46, v14, v21
	s_waitcnt lgkmcnt(0)
	v_add_f32_e32 v21, v21, v46
	ds_bpermute_b32 v46, v15, v21
	s_waitcnt lgkmcnt(0)
	v_add_f32_e32 v21, v21, v46
	ds_bpermute_b32 v46, v16, v21
	s_waitcnt lgkmcnt(0)
	v_add_f32_e32 v21, v21, v46
	ds_bpermute_b32 v46, v17, v21
	s_waitcnt lgkmcnt(0)
	v_add_f32_e32 v21, v21, v46
	v_fmamk_f32 v31, v21, 0xba800000, v31
	v_fmac_f32_e32 v30, 0xba800000, v21
	v_fmamk_f32 v33, v21, 0xba800000, v33
	v_fmac_f32_e32 v32, 0xba800000, v21
	v_fmamk_f32 v35, v21, 0xba800000, v35
	v_fmac_f32_e32 v34, 0xba800000, v21
	v_fmamk_f32 v37, v21, 0xba800000, v37
	v_fmac_f32_e32 v36, 0xba800000, v21
	v_pk_mul_f32 v[46:47], v[32:33], v[32:33]
	v_pk_mul_f32 v[48:49], v[30:31], v[30:31]
	v_pk_mul_f32 v[50:51], v[36:37], v[36:37]
	v_pk_mul_f32 v[52:53], v[34:35], v[34:35]
	v_fmac_f32_e32 v38, 0xba800000, v21
	v_fmac_f32_e32 v40, 0xba800000, v21
	v_pk_mov_b32 v[58:59], v[48:49], v[46:47] op_sel:[1,0]
	v_mov_b32_e32 v49, v47
	v_pk_mov_b32 v[46:47], v[52:53], v[50:51] op_sel:[1,0]
	v_mov_b32_e32 v53, v51
	v_fmamk_f32 v39, v21, 0xba800000, v39
	v_fmamk_f32 v41, v21, 0xba800000, v41
	v_mul_f32_e32 v54, v38, v38
	v_mul_f32_e32 v56, v40, v40
	v_pk_add_f32 v[48:49], v[58:59], v[48:49]
	v_pk_add_f32 v[46:47], v[46:47], v[52:53]
	v_fmamk_f32 v45, v21, 0xba800000, v45
	v_fmac_f32_e32 v44, 0xba800000, v21
	v_fmamk_f32 v43, v21, 0xba800000, v43
	v_fmac_f32_e32 v42, 0xba800000, v21
	v_pk_fma_f32 v[50:51], v[38:39], v[38:39], v[54:55] op_sel_hi:[1,1,0]
	v_pk_fma_f32 v[54:55], v[40:41], v[40:41], v[56:57] op_sel_hi:[1,1,0]
	v_pk_add_f32 v[48:49], v[48:49], v[48:49] op_sel_hi:[0,1]
	v_pk_add_f32 v[46:47], v[46:47], v[46:47] op_sel_hi:[0,1]
	v_mul_f32_e32 v50, v42, v42
	v_mul_f32_e32 v54, v43, v43
	v_mul_f32_e32 v48, v44, v44
	v_mul_f32_e32 v46, v45, v45
	v_pk_add_f32 v[50:51], v[50:51], v[54:55]
	v_pk_add_f32 v[46:47], v[48:49], v[46:47]
	s_nop 0
	v_pk_add_f32 v[46:47], v[50:51], v[46:47]
	v_mov_b32_e32 v51, 0
	v_add_f32_e32 v21, v46, v47
	ds_bpermute_b32 v46, v12, v21
	s_waitcnt lgkmcnt(0)
	v_add_f32_e32 v21, v21, v46
	ds_bpermute_b32 v46, v13, v21
	s_waitcnt lgkmcnt(0)
	v_add_f32_e32 v21, v21, v46
	ds_bpermute_b32 v46, v14, v21
	s_waitcnt lgkmcnt(0)
	v_add_f32_e32 v21, v21, v46
	ds_bpermute_b32 v46, v15, v21
	s_waitcnt lgkmcnt(0)
	v_add_f32_e32 v21, v21, v46
	ds_bpermute_b32 v46, v16, v21
	s_waitcnt lgkmcnt(0)
	v_add_f32_e32 v21, v21, v46
	ds_bpermute_b32 v46, v17, v21
	s_waitcnt lgkmcnt(0)
	v_add_f32_e32 v21, v21, v46
	v_fmamk_f32 v21, v21, 0x3a800000, v18
	v_mul_f32_e32 v46, 0x4f800000, v21
	v_cmp_gt_f32_e32 vcc, s3, v21
	s_nop 1
	v_cndmask_b32_e32 v21, v21, v46, vcc
	v_sqrt_f32_e32 v46, v21
	s_nop 0
	v_add_u32_e32 v47, -1, v46
	v_add_u32_e32 v48, 1, v46
	v_fma_f32 v49, -v47, v46, v21
	v_fma_f32 v50, -v48, v46, v21
	v_cmp_ge_f32_e64 s[0:1], 0, v49
	s_nop 1
	v_cndmask_b32_e64 v46, v46, v47, s[0:1]
	v_cmp_lt_f32_e64 s[0:1], 0, v50
	s_nop 1
	v_cndmask_b32_e64 v46, v46, v48, s[0:1]
	v_mul_f32_e32 v47, 0x37800000, v46
	v_cndmask_b32_e32 v46, v46, v47, vcc
	v_cmp_class_f32_e32 vcc, v21, v19
	s_nop 1
	v_cndmask_b32_e32 v21, v46, v21, vcc
	v_div_scale_f32 v46, s[0:1], v21, v21, 1.0
	v_rcp_f32_e32 v48, v46
	v_div_scale_f32 v47, vcc, 1.0, v21, 1.0
	v_fma_f32 v49, -v46, v48, 1.0
	v_fmac_f32_e32 v48, v49, v48
	v_mul_f32_e32 v49, v47, v48
	v_fma_f32 v50, -v46, v49, v47
	v_fmac_f32_e32 v49, v50, v48
	v_fma_f32 v46, -v46, v49, v47
	v_div_fmas_f32 v46, v46, v48, v49
	v_div_fixup_f32 v46, v46, v21, 1.0
	v_pk_mul_f32 v[30:31], v[30:31], v[46:47] op_sel_hi:[1,0]
	v_pk_mul_f32 v[32:33], v[32:33], v[46:47] op_sel_hi:[1,0]
	v_pk_fma_f32 v[22:23], v[22:23], v[30:31], v[26:27]
	v_pk_fma_f32 v[24:25], v[24:25], v[32:33], v[28:29]
	global_store_dwordx4 v[10:11], v[22:25], off nt
	global_load_dwordx4 v[26:29], v[0:1], off offset:1024
	global_load_dwordx4 v[30:33], v[2:3], off offset:1024
	v_pk_mul_f32 v[34:35], v[34:35], v[46:47] op_sel_hi:[1,0]
	v_pk_mul_f32 v[36:37], v[36:37], v[46:47] op_sel_hi:[1,0]
	v_pk_mul_f32 v[38:39], v[38:39], v[46:47] op_sel_hi:[1,0]
	v_pk_mul_f32 v[40:41], v[40:41], v[46:47] op_sel_hi:[1,0]
	v_mov_b32_e32 v21, 0
	v_med3_f32 v22, v22, s12, v20
	v_med3_f32 v23, v23, s12, v20
	v_mov_b32_e32 v47, 0
	v_cvt_pk_fp8_f32 v21, v22, v23
	v_mov_b32_e32 v50, 0
	v_pk_mul_f32 v[42:43], v[42:43], v[46:47] op_sel_hi:[1,0]
	v_pk_mul_f32 v[44:45], v[44:45], v[46:47] op_sel_hi:[1,0]
	v_med3_f32 v24, v24, s12, v20
	v_med3_f32 v25, v25, s12, v20
	v_cvt_pk_fp8_f32 v21, v24, v25 op_sel:[0,0,1]
	v_lshl_add_u64 v[48:49], s[84:85], 0, v[4:5]
	v_add_co_u32_e32 v48, vcc, s13, v48
	v_lshl_add_u64 v[4:5], v[4:5], 0, s[4:5]
	s_nop 0
	v_addc_co_u32_e32 v49, vcc, 0, v49, vcc
	s_waitcnt vmcnt(0)
	v_pk_fma_f32 v[28:29], v[28:29], v[36:37], v[32:33]
	v_pk_fma_f32 v[26:27], v[26:27], v[34:35], v[30:31]
	global_store_dwordx4 v[10:11], v[26:29], off offset:1024 nt
	global_load_dwordx4 v[30:33], v[0:1], off offset:2048
	global_load_dwordx4 v[34:37], v[2:3], off offset:2048
	v_med3_f32 v22, v26, s12, v20
	v_med3_f32 v23, v27, s12, v20
	v_cvt_pk_fp8_f32 v47, v22, v23
	v_med3_f32 v24, v28, s12, v20
	v_med3_f32 v25, v29, s12, v20
	v_cvt_pk_fp8_f32 v47, v24, v25 op_sel:[0,0,1]
	s_waitcnt vmcnt(0)
	v_pk_fma_f32 v[32:33], v[32:33], v[40:41], v[36:37]
	v_pk_fma_f32 v[30:31], v[30:31], v[38:39], v[34:35]
	global_store_dwordx4 v[10:11], v[30:33], off offset:2048 nt
	global_load_dwordx4 v[34:37], v[0:1], off offset:3072
	global_load_dwordx4 v[38:41], v[2:3], off offset:3072
	v_med3_f32 v22, v30, s12, v20
	v_med3_f32 v23, v31, s12, v20
	v_cvt_pk_fp8_f32 v50, v22, v23
	v_med3_f32 v24, v32, s12, v20
	v_med3_f32 v25, v33, s12, v20
	v_cvt_pk_fp8_f32 v50, v24, v25 op_sel:[0,0,1]
	s_waitcnt vmcnt(0)
	v_pk_fma_f32 v[22:23], v[34:35], v[42:43], v[38:39]
	s_nop 0
	v_med3_f32 v26, v22, s12, v20
	v_med3_f32 v27, v23, s12, v20
	v_cvt_pk_fp8_f32 v51, v26, v27
	v_pk_fma_f32 v[24:25], v[36:37], v[44:45], v[40:41]
	global_store_dwordx4 v[10:11], v[22:25], off offset:3072 nt
	v_med3_f32 v10, v24, s12, v20
	v_med3_f32 v11, v25, s12, v20
	v_cvt_pk_fp8_f32 v51, v10, v11 op_sel:[0,0,1]
	global_store_dword v[48:49], v21, off
	global_store_dword v[48:49], v47, off offset:256
	global_store_dword v[48:49], v50, off offset:512
	global_store_dword v[48:49], v51, off offset:768
	s_cbranch_scc1 .LBB0_521
	v_readlane_b32 s81, v234, 49

.LBB0_724:
	v_lshl_add_u64 v[26:27], s[84:85], 0, v[4:5]
	v_add_co_u32_e32 v28, vcc, 0x14400000, v26
	v_lshl_add_u64 v[24:25], s[84:85], 0, v[6:7]
	s_nop 0
	v_addc_co_u32_e32 v29, vcc, 0, v27, vcc
	v_add_co_u32_e32 v42, vcc, 0x10400000, v24
	global_load_dwordx4 v[16:19], v[0:1], off
	global_load_dwordx4 v[20:23], v[2:3], off
	v_add_co_u32_e64 v40, s[0:1], s9, v26
	global_load_dwordx2 v[44:45], v[28:29], off nt
	global_load_dwordx2 v[46:47], v[28:29], off offset:512 nt
	global_load_dwordx2 v[48:49], v[28:29], off offset:1024 nt
	global_load_dwordx2 v[50:51], v[28:29], off offset:1536 nt
	v_addc_co_u32_e32 v43, vcc, 0, v25, vcc
	v_addc_co_u32_e64 v41, s[0:1], 0, v27, s[0:1]
	global_load_dwordx4 v[24:27], v[42:43], off nt
	global_load_dwordx4 v[28:31], v[42:43], off offset:1024 nt
	global_load_dwordx4 v[32:35], v[42:43], off offset:2048 nt
	global_load_dwordx4 v[36:39], v[42:43], off offset:3072 nt
	s_add_i32 s10, s10, s80
	v_lshl_add_u64 v[4:5], v[4:5], 0, s[4:5]
	v_lshl_add_u64 v[6:7], v[6:7], 0, s[6:7]
	s_cmpk_lt_i32 s10, 0x4000
	s_waitcnt vmcnt(7)
	v_lshlrev_b32_e32 v52, 16, v44
	v_and_b32_e32 v53, 0xffff0000, v44
	v_lshlrev_b32_e32 v44, 16, v45
	v_and_b32_e32 v45, 0xffff0000, v45
	s_waitcnt vmcnt(6)
	v_lshlrev_b32_e32 v54, 16, v46
	v_and_b32_e32 v55, 0xffff0000, v46
	v_lshlrev_b32_e32 v46, 16, v47
	v_and_b32_e32 v47, 0xffff0000, v47
	s_waitcnt vmcnt(5)
	v_lshlrev_b32_e32 v56, 16, v48
	v_and_b32_e32 v57, 0xffff0000, v48
	v_lshlrev_b32_e32 v48, 16, v49
	v_and_b32_e32 v49, 0xffff0000, v49
	s_waitcnt vmcnt(4)
	v_lshlrev_b32_e32 v58, 16, v50
	v_and_b32_e32 v59, 0xffff0000, v50
	v_lshlrev_b32_e32 v50, 16, v51
	v_and_b32_e32 v51, 0xffff0000, v51
	s_waitcnt vmcnt(3)
	v_pk_fma_f32 v[26:27], v[26:27], s[8:9], v[44:45] op_sel_hi:[1,0,1]
	v_pk_fma_f32 v[24:25], v[24:25], s[8:9], v[52:53] op_sel_hi:[1,0,1]
	s_waitcnt vmcnt(2)
	v_pk_fma_f32 v[30:31], v[30:31], s[8:9], v[46:47] op_sel_hi:[1,0,1]
	v_pk_fma_f32 v[28:29], v[28:29], s[8:9], v[54:55] op_sel_hi:[1,0,1]
	s_waitcnt vmcnt(1)
	v_pk_fma_f32 v[34:35], v[34:35], s[8:9], v[48:49] op_sel_hi:[1,0,1]
	s_waitcnt vmcnt(0)
	v_pk_fma_f32 v[38:39], v[38:39], s[8:9], v[50:51] op_sel_hi:[1,0,1]
	v_pk_mov_b32 v[44:45], v[24:25], v[26:27] op_sel:[1,0]
	v_mov_b32_e32 v46, v24
	v_mov_b32_e32 v47, v27
	v_pk_mov_b32 v[48:49], v[28:29], v[30:31] op_sel:[1,0]
	v_mov_b32_e32 v50, v28
	v_mov_b32_e32 v51, v31
	v_pk_add_f32 v[44:45], v[44:45], v[46:47]
	v_pk_add_f32 v[46:47], v[48:49], v[50:51]
	v_pk_fma_f32 v[32:33], v[32:33], s[8:9], v[56:57] op_sel_hi:[1,0,1]
	v_pk_fma_f32 v[36:37], v[36:37], s[8:9], v[58:59] op_sel_hi:[1,0,1]
	v_add_f32_e32 v50, v44, v45
	v_pk_add_f32 v[44:45], v[46:47], v[46:47] op_sel:[0,1] op_sel_hi:[1,0]
	v_add_f32_e32 v52, v32, v33
	v_add_f32_e32 v54, v34, v35
	v_mov_b32_e32 v57, v36
	v_mov_b32_e32 v53, v38
	v_mov_b32_e32 v55, v39
	v_add_f32_e32 v56, 0, v50
	v_mov_b32_e32 v45, v37
	v_pk_add_f32 v[48:49], v[52:53], v[54:55]
	v_pk_add_f32 v[44:45], v[56:57], v[44:45]
	s_nop 0
	v_pk_add_f32 v[44:45], v[44:45], v[48:49]
	s_nop 0
	v_add_f32_e32 v44, v44, v45
	ds_bpermute_b32 v45, v8, v44
	s_waitcnt lgkmcnt(0)
	v_add_f32_e32 v44, v44, v45
	ds_bpermute_b32 v45, v9, v44
	s_waitcnt lgkmcnt(0)
	v_add_f32_e32 v44, v44, v45
	ds_bpermute_b32 v45, v10, v44
	s_waitcnt lgkmcnt(0)
	v_add_f32_e32 v44, v44, v45
	ds_bpermute_b32 v45, v11, v44
	s_waitcnt lgkmcnt(0)
	v_add_f32_e32 v44, v44, v45
	ds_bpermute_b32 v45, v12, v44
	s_waitcnt lgkmcnt(0)
	v_add_f32_e32 v44, v44, v45
	ds_bpermute_b32 v45, v13, v44
	s_waitcnt lgkmcnt(0)
	v_add_f32_e32 v44, v44, v45
	v_fmamk_f32 v25, v44, 0xba800000, v25
	v_fmac_f32_e32 v24, 0xba800000, v44
	v_fmamk_f32 v27, v44, 0xba800000, v27
	v_fmac_f32_e32 v26, 0xba800000, v44
	v_fmamk_f32 v29, v44, 0xba800000, v29
	v_fmac_f32_e32 v28, 0xba800000, v44
	v_fmamk_f32 v31, v44, 0xba800000, v31
	v_fmac_f32_e32 v30, 0xba800000, v44
	v_fmamk_f32 v33, v44, 0xba800000, v33
	v_fmac_f32_e32 v32, 0xba800000, v44
	v_fmamk_f32 v35, v44, 0xba800000, v35
	v_fmac_f32_e32 v34, 0xba800000, v44
	v_fmamk_f32 v39, v44, 0xba800000, v39
	v_fmac_f32_e32 v38, 0xba800000, v44
	v_fmamk_f32 v37, v44, 0xba800000, v37
	v_fmac_f32_e32 v36, 0xba800000, v44
	v_pk_mul_f32 v[44:45], v[26:27], v[26:27]
	v_pk_mul_f32 v[46:47], v[24:25], v[24:25]
	v_pk_mul_f32 v[48:49], v[30:31], v[30:31]
	v_pk_mul_f32 v[50:51], v[28:29], v[28:29]
	v_pk_mov_b32 v[56:57], v[46:47], v[44:45] op_sel:[1,0]
	v_mov_b32_e32 v47, v45
	v_pk_mov_b32 v[44:45], v[50:51], v[48:49] op_sel:[1,0]
	v_mov_b32_e32 v51, v49
	v_mul_f32_e32 v52, v32, v32
	v_mul_f32_e32 v54, v34, v34
	v_pk_add_f32 v[46:47], v[56:57], v[46:47]
	v_pk_add_f32 v[44:45], v[44:45], v[50:51]
	v_pk_fma_f32 v[48:49], v[32:33], v[32:33], v[52:53] op_sel_hi:[1,1,0]
	v_pk_fma_f32 v[52:53], v[34:35], v[34:35], v[54:55] op_sel_hi:[1,1,0]
	v_pk_add_f32 v[46:47], v[46:47], v[46:47] op_sel_hi:[0,1]
	v_pk_add_f32 v[44:45], v[44:45], v[44:45] op_sel_hi:[0,1]
	v_mul_f32_e32 v48, v36, v36
	v_mul_f32_e32 v52, v37, v37
	v_mul_f32_e32 v46, v38, v38
	v_mul_f32_e32 v44, v39, v39
	v_pk_add_f32 v[48:49], v[48:49], v[52:53]
	v_pk_add_f32 v[44:45], v[46:47], v[44:45]
	s_nop 0
	v_pk_add_f32 v[44:45], v[48:49], v[44:45]
	s_nop 0
	v_add_f32_e32 v44, v44, v45
	ds_bpermute_b32 v45, v8, v44
	s_waitcnt lgkmcnt(0)
	v_add_f32_e32 v44, v44, v45
	ds_bpermute_b32 v45, v9, v44
	s_waitcnt lgkmcnt(0)
	v_add_f32_e32 v44, v44, v45
	ds_bpermute_b32 v45, v10, v44
	s_waitcnt lgkmcnt(0)
	v_add_f32_e32 v44, v44, v45
	ds_bpermute_b32 v45, v11, v44
	s_waitcnt lgkmcnt(0)
	v_add_f32_e32 v44, v44, v45
	ds_bpermute_b32 v45, v12, v44
	s_waitcnt lgkmcnt(0)
	v_add_f32_e32 v44, v44, v45
	ds_bpermute_b32 v45, v13, v44
	s_waitcnt lgkmcnt(0)
	v_add_f32_e32 v44, v44, v45
	v_fmamk_f32 v44, v44, 0x3a800000, v14
	v_mul_f32_e32 v45, 0x4f800000, v44
	v_cmp_gt_f32_e32 vcc, s3, v44
	s_nop 1
	v_cndmask_b32_e32 v44, v44, v45, vcc
	v_sqrt_f32_e32 v45, v44
	s_nop 0
	v_add_u32_e32 v46, -1, v45
	v_add_u32_e32 v47, 1, v45
	v_fma_f32 v48, -v46, v45, v44
	v_fma_f32 v49, -v47, v45, v44
	v_cmp_ge_f32_e64 s[0:1], 0, v48
	s_nop 1
	v_cndmask_b32_e64 v45, v45, v46, s[0:1]
	v_cmp_lt_f32_e64 s[0:1], 0, v49
	s_nop 1
	v_cndmask_b32_e64 v45, v45, v47, s[0:1]
	v_mul_f32_e32 v46, 0x37800000, v45
	v_cndmask_b32_e32 v45, v45, v46, vcc
	v_cmp_class_f32_e32 vcc, v44, v15
	s_nop 1
	v_cndmask_b32_e32 v44, v45, v44, vcc
	v_div_scale_f32 v45, s[0:1], v44, v44, 1.0
	v_rcp_f32_e32 v47, v45
	v_div_scale_f32 v46, vcc, 1.0, v44, 1.0
	v_fma_f32 v48, -v45, v47, 1.0
	v_fmac_f32_e32 v47, v48, v47
	v_mul_f32_e32 v48, v46, v47
	v_fma_f32 v49, -v45, v48, v46
	v_fmac_f32_e32 v48, v49, v47
	v_fma_f32 v45, -v45, v48, v46
	v_div_fmas_f32 v45, v45, v47, v48
	v_div_fixup_f32 v44, v45, v44, 1.0
	v_pk_mul_f32 v[24:25], v[24:25], v[44:45] op_sel_hi:[1,0]
	v_pk_mul_f32 v[26:27], v[26:27], v[44:45] op_sel_hi:[1,0]
	v_pk_fma_f32 v[16:17], v[16:17], v[24:25], v[20:21]
	v_pk_fma_f32 v[18:19], v[18:19], v[26:27], v[22:23]
	global_store_dwordx4 v[42:43], v[16:19], off nt
	v_pk_mul_f32 v[24:25], v[30:31], v[44:45] op_sel_hi:[1,0]
	v_pk_mul_f32 v[26:27], v[28:29], v[44:45] op_sel_hi:[1,0]
	v_cvt_pk_bf16_f32 v16, v16, v17
	v_cvt_pk_bf16_f32 v17, v18, v19
	global_store_dwordx2 v[40:41], v[16:17], off
	global_load_dwordx4 v[16:19], v[0:1], off offset:1024
	s_nop 0
	global_load_dwordx4 v[20:23], v[2:3], off offset:1024
	s_waitcnt vmcnt(0)
	v_pk_fma_f32 v[16:17], v[16:17], v[26:27], v[20:21]
	v_pk_fma_f32 v[18:19], v[18:19], v[24:25], v[22:23]
	global_store_dwordx4 v[42:43], v[16:19], off offset:1024 nt
	v_pk_mul_f32 v[24:25], v[34:35], v[44:45] op_sel_hi:[1,0]
	v_pk_mul_f32 v[26:27], v[32:33], v[44:45] op_sel_hi:[1,0]
	v_cvt_pk_bf16_f32 v16, v16, v17
	v_cvt_pk_bf16_f32 v17, v18, v19
	global_store_dwordx2 v[40:41], v[16:17], off offset:512
	global_load_dwordx4 v[16:19], v[0:1], off offset:2048
	s_nop 0
	global_load_dwordx4 v[20:23], v[2:3], off offset:2048
	s_waitcnt vmcnt(0)
	v_pk_fma_f32 v[16:17], v[16:17], v[26:27], v[20:21]
	v_pk_fma_f32 v[18:19], v[18:19], v[24:25], v[22:23]
	global_store_dwordx4 v[42:43], v[16:19], off offset:2048 nt
	v_pk_mul_f32 v[24:25], v[38:39], v[44:45] op_sel_hi:[1,0]
	v_pk_mul_f32 v[26:27], v[36:37], v[44:45] op_sel_hi:[1,0]
	v_cvt_pk_bf16_f32 v16, v16, v17
	v_cvt_pk_bf16_f32 v17, v18, v19
	global_store_dwordx2 v[40:41], v[16:17], off offset:1024
	global_load_dwordx4 v[16:19], v[0:1], off offset:3072
	s_nop 0
	global_load_dwordx4 v[20:23], v[2:3], off offset:3072
	s_waitcnt vmcnt(0)
	v_pk_fma_f32 v[16:17], v[16:17], v[26:27], v[20:21]
	v_pk_fma_f32 v[18:19], v[18:19], v[24:25], v[22:23]
	global_store_dwordx4 v[42:43], v[16:19], off offset:3072 nt
	s_nop 1
	v_cvt_pk_bf16_f32 v16, v16, v17
	v_cvt_pk_bf16_f32 v17, v18, v19
	global_store_dwordx2 v[40:41], v[16:17], off offset:1536
	s_cbranch_scc1 .LBB0_724
	v_readlane_b32 s81, v234, 49

.LBB0_1060:
	v_lshl_add_u64 v[0:1], s[84:85], 0, v[24:25]
	v_add_co_u32_e32 v0, vcc, 0x14400000, v0
	s_waitcnt lgkmcnt(6)
	v_lshl_add_u64 v[2:3], s[84:85], 0, v[22:23]
	v_addc_co_u32_e32 v1, vcc, 0, v1, vcc
	global_load_dwordx2 v[4:5], v[0:1], off nt
	s_waitcnt lgkmcnt(0)
	global_load_dwordx2 v[14:15], v[0:1], off offset:512 nt
	global_load_dwordx2 v[28:29], v[0:1], off offset:1024 nt
	v_add_co_u32_e32 v26, vcc, 0x10400000, v2
	global_load_dwordx2 v[30:31], v[0:1], off offset:1536 nt
	s_nop 0
	v_addc_co_u32_e32 v27, vcc, 0, v3, vcc
	global_load_dwordx4 v[0:3], v[26:27], off nt
	global_load_dwordx4 v[6:9], v[26:27], off offset:1024 nt
	global_load_dwordx4 v[10:13], v[26:27], off offset:2048 nt
	global_load_dwordx4 v[56:59], v[26:27], off offset:3072 nt
	s_waitcnt vmcnt(7)
	v_lshlrev_b32_e32 v32, 16, v4
	v_and_b32_e32 v33, 0xffff0000, v4
	v_lshlrev_b32_e32 v4, 16, v5
	v_and_b32_e32 v5, 0xffff0000, v5
	s_waitcnt vmcnt(6)
	v_lshlrev_b32_e32 v34, 16, v14
	v_and_b32_e32 v35, 0xffff0000, v14
	v_lshlrev_b32_e32 v14, 16, v15
	v_and_b32_e32 v15, 0xffff0000, v15
	s_waitcnt vmcnt(5)
	v_lshlrev_b32_e32 v38, 16, v28
	v_and_b32_e32 v39, 0xffff0000, v28
	v_lshlrev_b32_e32 v28, 16, v29
	v_and_b32_e32 v29, 0xffff0000, v29
	s_waitcnt vmcnt(3)
	v_pk_fma_f32 v[4:5], v[2:3], s[30:31], v[4:5] op_sel_hi:[1,0,1]
	v_pk_fma_f32 v[64:65], v[0:1], s[30:31], v[32:33] op_sel_hi:[1,0,1]
	s_waitcnt vmcnt(2)
	v_pk_fma_f32 v[0:1], v[8:9], s[30:31], v[14:15] op_sel_hi:[1,0,1]
	v_pk_fma_f32 v[2:3], v[6:7], s[30:31], v[34:35] op_sel_hi:[1,0,1]
	v_lshlrev_b32_e32 v60, 16, v30
	v_and_b32_e32 v61, 0xffff0000, v30
	v_lshlrev_b32_e32 v62, 16, v31
	v_and_b32_e32 v63, 0xffff0000, v31
	s_waitcnt vmcnt(1)
	v_pk_fma_f32 v[28:29], v[12:13], s[30:31], v[28:29] op_sel_hi:[1,0,1]
	v_pk_fma_f32 v[30:31], v[10:11], s[30:31], v[38:39] op_sel_hi:[1,0,1]
	v_pk_mov_b32 v[6:7], v[64:65], v[4:5] op_sel:[1,0]
	v_mov_b32_e32 v8, v64
	v_mov_b32_e32 v9, v5
	v_pk_mov_b32 v[10:11], v[2:3], v[0:1] op_sel:[1,0]
	v_mov_b32_e32 v12, v2
	v_mov_b32_e32 v13, v1
	v_pk_add_f32 v[6:7], v[6:7], v[8:9]
	v_pk_add_f32 v[8:9], v[10:11], v[12:13]
	s_waitcnt vmcnt(0)
	v_pk_fma_f32 v[32:33], v[58:59], s[30:31], v[62:63] op_sel_hi:[1,0,1]
	v_pk_fma_f32 v[34:35], v[56:57], s[30:31], v[60:61] op_sel_hi:[1,0,1]
	v_add_f32_e32 v12, v6, v7
	v_pk_add_f32 v[6:7], v[8:9], v[8:9] op_sel:[0,1] op_sel_hi:[1,0]
	v_add_f32_e32 v14, v30, v31
	v_add_f32_e32 v38, v28, v29
	v_mov_b32_e32 v57, v34
	v_mov_b32_e32 v15, v32
	v_mov_b32_e32 v39, v33
	v_add_f32_e32 v56, 0, v12
	v_mov_b32_e32 v7, v35
	v_pk_add_f32 v[10:11], v[14:15], v[38:39]
	v_pk_add_f32 v[6:7], v[56:57], v[6:7]
	s_nop 0
	v_pk_add_f32 v[6:7], v[6:7], v[10:11]
	global_load_dwordx4 v[8:11], v[16:17], off
	global_load_dwordx4 v[12:15], v[18:19], off
	v_add_f32_e32 v6, v6, v7
	ds_bpermute_b32 v7, v40, v6
	s_waitcnt lgkmcnt(0)
	v_add_f32_e32 v6, v6, v7
	ds_bpermute_b32 v7, v41, v6
	s_waitcnt lgkmcnt(0)
	v_add_f32_e32 v6, v6, v7
	ds_bpermute_b32 v7, v42, v6
	s_waitcnt lgkmcnt(0)
	v_add_f32_e32 v6, v6, v7
	ds_bpermute_b32 v7, v43, v6
	s_waitcnt lgkmcnt(0)
	v_add_f32_e32 v6, v6, v7
	ds_bpermute_b32 v7, v44, v6
	s_waitcnt lgkmcnt(0)
	v_add_f32_e32 v6, v6, v7
	ds_bpermute_b32 v7, v45, v6
	s_waitcnt lgkmcnt(0)
	v_add_f32_e32 v6, v6, v7
	v_fmamk_f32 v65, v6, 0xba800000, v65
	v_fmac_f32_e32 v64, 0xba800000, v6
	v_fmamk_f32 v5, v6, 0xba800000, v5
	v_fmac_f32_e32 v4, 0xba800000, v6
	v_fmamk_f32 v3, v6, 0xba800000, v3
	v_fmac_f32_e32 v2, 0xba800000, v6
	v_fmamk_f32 v1, v6, 0xba800000, v1
	v_fmac_f32_e32 v0, 0xba800000, v6
	v_fmamk_f32 v31, v6, 0xba800000, v31
	v_fmac_f32_e32 v30, 0xba800000, v6
	v_fmamk_f32 v29, v6, 0xba800000, v29
	v_fmac_f32_e32 v28, 0xba800000, v6
	v_fmamk_f32 v33, v6, 0xba800000, v33
	v_fmac_f32_e32 v32, 0xba800000, v6
	v_fmamk_f32 v35, v6, 0xba800000, v35
	v_fmac_f32_e32 v34, 0xba800000, v6
	v_pk_mul_f32 v[6:7], v[4:5], v[4:5]
	v_pk_mul_f32 v[38:39], v[64:65], v[64:65]
	v_pk_mul_f32 v[56:57], v[0:1], v[0:1]
	v_pk_mul_f32 v[58:59], v[2:3], v[2:3]
	v_pk_mov_b32 v[62:63], v[38:39], v[6:7] op_sel:[1,0]
	v_mov_b32_e32 v39, v7
	v_pk_mov_b32 v[6:7], v[58:59], v[56:57] op_sel:[1,0]
	v_mov_b32_e32 v59, v57
	v_mul_f32_e32 v36, v30, v30
	v_mul_f32_e32 v60, v28, v28
	v_pk_add_f32 v[38:39], v[62:63], v[38:39]
	v_pk_add_f32 v[6:7], v[6:7], v[58:59]
	v_pk_fma_f32 v[56:57], v[30:31], v[30:31], v[36:37] op_sel_hi:[1,1,0]
	v_pk_fma_f32 v[60:61], v[28:29], v[28:29], v[60:61] op_sel_hi:[1,1,0]
	v_pk_add_f32 v[38:39], v[38:39], v[38:39] op_sel_hi:[0,1]
	v_pk_add_f32 v[6:7], v[6:7], v[6:7] op_sel_hi:[0,1]
	v_mul_f32_e32 v56, v34, v34
	v_mul_f32_e32 v60, v35, v35
	v_mul_f32_e32 v38, v32, v32
	v_mul_f32_e32 v6, v33, v33
	v_pk_add_f32 v[56:57], v[56:57], v[60:61]
	v_pk_add_f32 v[6:7], v[38:39], v[6:7]
	v_mov_b32_e32 v58, 0
	v_pk_add_f32 v[6:7], v[56:57], v[6:7]
	v_mov_b32_e32 v57, 0
	v_add_f32_e32 v6, v6, v7
	ds_bpermute_b32 v7, v40, v6
	v_mov_b32_e32 v56, 0
	s_waitcnt lgkmcnt(0)
	v_add_f32_e32 v6, v6, v7
	ds_bpermute_b32 v7, v41, v6
	s_waitcnt lgkmcnt(0)
	v_add_f32_e32 v6, v6, v7
	ds_bpermute_b32 v7, v42, v6
	s_waitcnt lgkmcnt(0)
	v_add_f32_e32 v6, v6, v7
	ds_bpermute_b32 v7, v43, v6
	s_waitcnt lgkmcnt(0)
	v_add_f32_e32 v6, v6, v7
	ds_bpermute_b32 v7, v44, v6
	s_waitcnt lgkmcnt(0)
	v_add_f32_e32 v6, v6, v7
	ds_bpermute_b32 v7, v45, v6
	s_waitcnt lgkmcnt(0)
	v_add_f32_e32 v6, v6, v7
	v_fmamk_f32 v6, v6, 0x3a800000, v48
	v_mul_f32_e32 v7, 0x4f800000, v6
	v_cmp_gt_f32_e32 vcc, s23, v6
	s_nop 1
	v_cndmask_b32_e32 v6, v6, v7, vcc
	v_sqrt_f32_e32 v7, v6
	s_nop 0
	v_add_u32_e32 v36, -1, v7
	v_add_u32_e32 v38, 1, v7
	v_fma_f32 v39, -v36, v7, v6
	v_fma_f32 v55, -v38, v7, v6
	v_cmp_ge_f32_e64 s[6:7], 0, v39
	s_nop 1
	v_cndmask_b32_e64 v7, v7, v36, s[6:7]
	v_cmp_lt_f32_e64 s[6:7], 0, v55
	s_nop 1
	v_cndmask_b32_e64 v7, v7, v38, s[6:7]
	v_mul_f32_e32 v36, 0x37800000, v7
	v_cndmask_b32_e32 v7, v7, v36, vcc
	v_cmp_class_f32_e32 vcc, v6, v49
	s_nop 1
	v_cndmask_b32_e32 v6, v7, v6, vcc
	v_div_scale_f32 v7, s[6:7], v6, v6, 1.0
	v_rcp_f32_e32 v36, v7
	v_div_scale_f32 v38, vcc, 1.0, v6, 1.0
	v_fma_f32 v39, -v7, v36, 1.0
	v_fmac_f32_e32 v36, v39, v36
	v_mul_f32_e32 v39, v38, v36
	v_fma_f32 v55, -v7, v39, v38
	v_fmac_f32_e32 v39, v55, v36
	v_fma_f32 v7, -v7, v39, v38
	v_div_fmas_f32 v7, v7, v36, v39
	v_div_fixup_f32 v36, v7, v6, 1.0
	v_pk_mul_f32 v[38:39], v[64:65], v[36:37] op_sel_hi:[1,0]
	v_pk_mul_f32 v[4:5], v[4:5], v[36:37] op_sel_hi:[1,0]
	v_pk_mul_f32 v[0:1], v[0:1], v[36:37] op_sel_hi:[1,0]
	s_waitcnt vmcnt(0)
	v_pk_fma_f32 v[6:7], v[10:11], v[4:5], v[14:15]
	v_pk_fma_f32 v[4:5], v[8:9], v[38:39], v[12:13]
	global_store_dwordx4 v[26:27], v[4:7], off nt
	global_load_dwordx4 v[8:11], v[16:17], off offset:1024
	global_load_dwordx4 v[12:15], v[18:19], off offset:1024
	v_pk_mul_f32 v[38:39], v[2:3], v[36:37] op_sel_hi:[1,0]
	v_pk_mul_f32 v[30:31], v[30:31], v[36:37] op_sel_hi:[1,0]
	v_pk_mul_f32 v[28:29], v[28:29], v[36:37] op_sel_hi:[1,0]
	v_pk_mul_f32 v[34:35], v[34:35], v[36:37] op_sel_hi:[1,0]
	v_pk_mul_f32 v[32:33], v[32:33], v[36:37] op_sel_hi:[1,0]
	v_med3_f32 v36, v4, s31, v50
	v_med3_f32 v59, v5, s31, v50
	v_med3_f32 v187, v6, s31, v50
	v_med3_f32 v196, v7, s31, v50
	v_mov_b32_e32 v55, 0
	v_cvt_pk_fp8_f32 v55, v36, v59
	v_cvt_pk_fp8_f32 v55, v187, v196 op_sel:[0,0,1]
	s_waitcnt vmcnt(0)
	v_pk_fma_f32 v[2:3], v[10:11], v[0:1], v[14:15]
	v_pk_fma_f32 v[0:1], v[8:9], v[38:39], v[12:13]
	global_store_dwordx4 v[26:27], v[0:3], off offset:1024 nt
	global_load_dwordx4 v[8:11], v[16:17], off offset:2048
	global_load_dwordx4 v[12:15], v[18:19], off offset:2048
	ds_read_b128 v[60:63], v51
	ds_read_b128 v[64:67], v51 offset:16
	ds_read_b128 v[68:71], v51 offset:32
	ds_read_b128 v[72:75], v51 offset:48
	ds_read_b128 v[76:79], v51 offset:64
	ds_read_b128 v[80:83], v51 offset:80
	ds_read_b128 v[84:87], v51 offset:96
	ds_read_b128 v[88:91], v51 offset:112
	ds_read_b128 v[92:95], v51 offset:8192
	ds_read_b128 v[96:99], v51 offset:8208
	ds_read_b128 v[100:103], v51 offset:8224
	ds_read_b128 v[104:107], v51 offset:8240
	ds_read_b128 v[108:111], v51 offset:8256
	ds_read_b128 v[112:115], v51 offset:8272
	ds_read_b128 v[116:119], v51 offset:8288
	ds_read_b128 v[120:123], v51 offset:8304
	ds_read_b128 v[124:127], v51 offset:16384
	ds_read_b128 v[128:131], v51 offset:16400
	ds_read_b128 v[132:135], v51 offset:16416
	ds_read_b128 v[136:139], v51 offset:16432
	ds_read_b128 v[140:143], v51 offset:16448
	ds_read_b128 v[144:147], v51 offset:16464
	ds_read_b128 v[148:151], v51 offset:16480
	ds_read_b128 v[152:155], v51 offset:16496
	ds_read_b128 v[156:159], v51 offset:24576
	ds_read_b128 v[164:167], v51 offset:24592
	ds_read_b128 v[168:171], v51 offset:24608
	ds_read_b128 v[172:175], v51 offset:24624
	ds_read_b128 v[176:179], v51 offset:24640
	ds_read_b128 v[180:183], v51 offset:24656
	ds_read_b128 v[188:191], v51 offset:24672
	ds_read_b128 v[192:195], v51 offset:24688
	s_waitcnt lgkmcnt(14)
	v_fma_f32 v62, v62, v4, 0
	v_fma_f32 v63, v63, v4, 0
	v_fma_f32 v64, v64, v4, 0
	v_fma_f32 v65, v65, v4, 0
	v_fma_f32 v66, v66, v4, 0
	v_fma_f32 v67, v67, v4, 0
	v_pk_fma_f32 v[60:61], v[60:61], v[4:5], 0 op_sel_hi:[1,0,0]
	v_fmac_f32_e32 v62, v70, v5
	v_fmac_f32_e32 v63, v71, v5
	v_fmac_f32_e32 v64, v72, v5
	v_fmac_f32_e32 v65, v73, v5
	v_fmac_f32_e32 v66, v74, v5
	v_fmac_f32_e32 v67, v75, v5
	v_pk_fma_f32 v[4:5], v[68:69], v[4:5], v[60:61] op_sel:[0,1,0]
	v_fmac_f32_e32 v62, v78, v6
	v_fmac_f32_e32 v63, v79, v6
	v_fmac_f32_e32 v64, v80, v6
	v_fmac_f32_e32 v65, v81, v6
	v_fmac_f32_e32 v66, v82, v6
	v_fmac_f32_e32 v67, v83, v6
	v_pk_fma_f32 v[4:5], v[76:77], v[6:7], v[4:5] op_sel_hi:[1,0,1]
	v_fmac_f32_e32 v62, v7, v86
	v_fmac_f32_e32 v63, v7, v87
	v_fmac_f32_e32 v64, v7, v88
	v_fmac_f32_e32 v65, v7, v89
	v_fmac_f32_e32 v66, v7, v90
	v_fmac_f32_e32 v67, v7, v91
	v_pk_fma_f32 v[4:5], v[6:7], v[84:85], v[4:5] op_sel:[1,0,0]
	v_fmac_f32_e32 v62, v0, v94
	v_fmac_f32_e32 v63, v0, v95
	v_fmac_f32_e32 v64, v0, v96
	v_fmac_f32_e32 v65, v0, v97
	v_fmac_f32_e32 v66, v0, v98
	v_fmac_f32_e32 v67, v0, v99
	v_pk_fma_f32 v[4:5], v[0:1], v[92:93], v[4:5] op_sel_hi:[0,1,1]
	v_med3_f32 v6, v0, s31, v50
	v_med3_f32 v7, v1, s31, v50
	v_fmac_f32_e32 v62, v1, v102
	v_fmac_f32_e32 v63, v1, v103
	v_fmac_f32_e32 v64, v1, v104
	v_fmac_f32_e32 v65, v1, v105
	v_fmac_f32_e32 v66, v1, v106
	v_fmac_f32_e32 v67, v1, v107
	v_pk_fma_f32 v[0:1], v[0:1], v[100:101], v[4:5] op_sel:[1,0,0]
	v_fmac_f32_e32 v62, v2, v110
	v_fmac_f32_e32 v63, v2, v111
	v_fmac_f32_e32 v64, v2, v112
	v_fmac_f32_e32 v65, v2, v113
	v_fmac_f32_e32 v66, v2, v114
	v_fmac_f32_e32 v67, v2, v115
	v_pk_fma_f32 v[0:1], v[2:3], v[108:109], v[0:1] op_sel_hi:[0,1,1]
	v_fmac_f32_e32 v62, v3, v118
	v_fmac_f32_e32 v63, v3, v119
	v_fmac_f32_e32 v64, v3, v120
	v_fmac_f32_e32 v65, v3, v121
	v_fmac_f32_e32 v66, v3, v122
	v_fmac_f32_e32 v67, v3, v123
	v_pk_fma_f32 v[0:1], v[2:3], v[116:117], v[0:1] op_sel:[1,0,0]
	v_med3_f32 v36, v2, s31, v50
	v_med3_f32 v59, v3, s31, v50
	v_cvt_pk_fp8_f32 v56, v6, v7
	v_lshl_add_u64 v[38:39], s[84:85], 0, v[20:21]
	v_add_co_u32_e32 v38, vcc, s36, v38
	v_cvt_pk_fp8_f32 v56, v36, v59 op_sel:[0,0,1]
	s_nop 0
	v_addc_co_u32_e32 v39, vcc, 0, v39, vcc
	s_waitcnt vmcnt(0)
	v_pk_fma_f32 v[10:11], v[10:11], v[28:29], v[14:15]
	v_pk_fma_f32 v[8:9], v[8:9], v[30:31], v[12:13]
	global_store_dwordx4 v[26:27], v[8:11], off offset:2048 nt
	global_load_dwordx4 v[12:15], v[16:17], off offset:3072
	global_load_dwordx4 v[28:31], v[18:19], off offset:3072
	v_med3_f32 v2, v8, s31, v50
	v_med3_f32 v3, v9, s31, v50
	v_fmac_f32_e32 v62, v8, v126
	v_fmac_f32_e32 v63, v8, v127
	v_fmac_f32_e32 v64, v8, v128
	v_fmac_f32_e32 v65, v8, v129
	v_fmac_f32_e32 v66, v8, v130
	v_fmac_f32_e32 v67, v8, v131
	v_pk_fma_f32 v[0:1], v[8:9], v[124:125], v[0:1] op_sel_hi:[0,1,1]
	v_cvt_pk_fp8_f32 v57, v2, v3
	s_waitcnt lgkmcnt(13)
	v_pk_fma_f32 v[0:1], v[8:9], v[132:133], v[0:1] op_sel:[1,0,0]
	v_fmac_f32_e32 v62, v9, v134
	v_fmac_f32_e32 v63, v9, v135
	s_waitcnt lgkmcnt(12)
	v_fmac_f32_e32 v64, v9, v136
	v_fmac_f32_e32 v65, v9, v137
	v_fmac_f32_e32 v66, v9, v138
	v_fmac_f32_e32 v67, v9, v139
	s_waitcnt lgkmcnt(11)
	v_fmac_f32_e32 v62, v10, v142
	v_fmac_f32_e32 v63, v10, v143
	s_waitcnt lgkmcnt(10)
	v_fmac_f32_e32 v64, v10, v144
	v_fmac_f32_e32 v65, v10, v145
	v_fmac_f32_e32 v66, v10, v146
	v_fmac_f32_e32 v67, v10, v147
	v_pk_fma_f32 v[0:1], v[10:11], v[140:141], v[0:1] op_sel_hi:[0,1,1]
	s_waitcnt lgkmcnt(9)
	v_fmac_f32_e32 v62, v11, v150
	v_fmac_f32_e32 v63, v11, v151
	s_waitcnt lgkmcnt(8)
	v_fmac_f32_e32 v64, v11, v152
	v_fmac_f32_e32 v65, v11, v153
	v_fmac_f32_e32 v66, v11, v154
	v_fmac_f32_e32 v67, v11, v155
	v_pk_fma_f32 v[4:5], v[10:11], v[148:149], v[0:1] op_sel:[1,0,0]
	v_med3_f32 v6, v10, s31, v50
	v_med3_f32 v7, v11, s31, v50
	v_cvt_pk_fp8_f32 v57, v6, v7 op_sel:[0,0,1]
	s_waitcnt vmcnt(0)
	v_pk_fma_f32 v[0:1], v[12:13], v[34:35], v[28:29]
	v_pk_fma_f32 v[2:3], v[14:15], v[32:33], v[30:31]
	s_waitcnt lgkmcnt(7)
	v_fmac_f32_e32 v62, v0, v158
	v_fmac_f32_e32 v63, v0, v159
	s_waitcnt lgkmcnt(6)
	v_fmac_f32_e32 v64, v0, v164
	v_fmac_f32_e32 v65, v0, v165
	v_fmac_f32_e32 v66, v0, v166
	v_fmac_f32_e32 v67, v0, v167
	v_pk_fma_f32 v[4:5], v[0:1], v[156:157], v[4:5] op_sel_hi:[0,1,1]
	global_store_dwordx4 v[26:27], v[0:3], off offset:3072 nt
	v_med3_f32 v6, v0, s31, v50
	v_med3_f32 v7, v1, s31, v50
	s_waitcnt lgkmcnt(5)
	v_fmac_f32_e32 v62, v1, v170
	v_fmac_f32_e32 v63, v1, v171
	s_waitcnt lgkmcnt(4)
	v_fmac_f32_e32 v64, v1, v172
	v_fmac_f32_e32 v65, v1, v173
	v_fmac_f32_e32 v66, v1, v174
	v_fmac_f32_e32 v67, v1, v175
	v_pk_fma_f32 v[0:1], v[0:1], v[168:169], v[4:5] op_sel:[1,0,0]
	s_waitcnt lgkmcnt(3)
	v_fmac_f32_e32 v62, v2, v178
	v_fmac_f32_e32 v63, v2, v179
	s_waitcnt lgkmcnt(2)
	v_fmac_f32_e32 v64, v2, v180
	v_fmac_f32_e32 v65, v2, v181
	v_fmac_f32_e32 v66, v2, v182
	v_fmac_f32_e32 v67, v2, v183
	v_pk_fma_f32 v[0:1], v[2:3], v[176:177], v[0:1] op_sel_hi:[0,1,1]
	s_waitcnt lgkmcnt(1)
	v_fmac_f32_e32 v62, v3, v190
	v_fmac_f32_e32 v63, v3, v191
	s_waitcnt lgkmcnt(0)
	v_fmac_f32_e32 v64, v3, v192
	v_fmac_f32_e32 v65, v3, v193
	v_fmac_f32_e32 v66, v3, v194
	v_fmac_f32_e32 v67, v3, v195
	v_pk_fma_f32 v[0:1], v[2:3], v[188:189], v[0:1] op_sel:[1,0,0]
	v_med3_f32 v8, v2, s31, v50
	v_med3_f32 v9, v3, s31, v50
	v_cvt_pk_fp8_f32 v58, v6, v7
	ds_bpermute_b32 v2, v40, v0
	ds_bpermute_b32 v3, v40, v1
	ds_bpermute_b32 v4, v40, v62
	ds_bpermute_b32 v5, v40, v63
	ds_bpermute_b32 v6, v40, v64
	ds_bpermute_b32 v7, v40, v65
	ds_bpermute_b32 v10, v40, v66
	ds_bpermute_b32 v11, v40, v67
	v_cvt_pk_fp8_f32 v58, v8, v9 op_sel:[0,0,1]
	s_waitcnt lgkmcnt(6)
	v_pk_add_f32 v[0:1], v[0:1], v[2:3]
	s_waitcnt lgkmcnt(5)
	v_add_f32_e32 v4, v62, v4
	s_waitcnt lgkmcnt(4)
	v_add_f32_e32 v5, v63, v5
	s_waitcnt lgkmcnt(3)
	v_add_f32_e32 v6, v64, v6
	s_waitcnt lgkmcnt(2)
	v_add_f32_e32 v7, v65, v7
	s_waitcnt lgkmcnt(1)
	v_add_f32_e32 v8, v66, v10
	s_waitcnt lgkmcnt(0)
	v_add_f32_e32 v9, v67, v11
	ds_bpermute_b32 v2, v41, v0
	ds_bpermute_b32 v3, v41, v1
	ds_bpermute_b32 v10, v41, v4
	ds_bpermute_b32 v11, v41, v5
	ds_bpermute_b32 v12, v41, v6
	ds_bpermute_b32 v13, v41, v7
	ds_bpermute_b32 v14, v41, v8
	ds_bpermute_b32 v15, v41, v9
	s_waitcnt lgkmcnt(6)
	v_pk_add_f32 v[0:1], v[0:1], v[2:3]
	s_waitcnt lgkmcnt(5)
	v_add_f32_e32 v4, v4, v10
	s_waitcnt lgkmcnt(4)
	v_add_f32_e32 v5, v5, v11
	s_waitcnt lgkmcnt(3)
	v_add_f32_e32 v6, v6, v12
	s_waitcnt lgkmcnt(2)
	v_add_f32_e32 v7, v7, v13
	s_waitcnt lgkmcnt(1)
	v_add_f32_e32 v8, v8, v14
	s_waitcnt lgkmcnt(0)
	v_add_f32_e32 v9, v9, v15
	ds_bpermute_b32 v2, v42, v0
	ds_bpermute_b32 v3, v42, v1
	ds_bpermute_b32 v10, v42, v4
	ds_bpermute_b32 v11, v42, v5
	ds_bpermute_b32 v12, v42, v6
	ds_bpermute_b32 v13, v42, v7
	ds_bpermute_b32 v14, v42, v8
	ds_bpermute_b32 v15, v42, v9
	s_waitcnt lgkmcnt(6)
	v_pk_add_f32 v[0:1], v[0:1], v[2:3]
	s_waitcnt lgkmcnt(5)
	v_add_f32_e32 v4, v4, v10
	s_waitcnt lgkmcnt(4)
	v_add_f32_e32 v5, v5, v11
	s_waitcnt lgkmcnt(3)
	v_add_f32_e32 v6, v6, v12
	s_waitcnt lgkmcnt(2)
	v_add_f32_e32 v7, v7, v13
	s_waitcnt lgkmcnt(1)
	v_add_f32_e32 v8, v8, v14
	s_waitcnt lgkmcnt(0)
	v_add_f32_e32 v9, v9, v15
	ds_bpermute_b32 v2, v43, v0
	ds_bpermute_b32 v3, v43, v1
	ds_bpermute_b32 v10, v43, v4
	ds_bpermute_b32 v11, v43, v5
	ds_bpermute_b32 v12, v43, v6
	ds_bpermute_b32 v13, v43, v7
	ds_bpermute_b32 v14, v43, v8
	ds_bpermute_b32 v15, v43, v9
	s_waitcnt lgkmcnt(6)
	v_pk_add_f32 v[0:1], v[0:1], v[2:3]
	s_waitcnt lgkmcnt(5)
	v_add_f32_e32 v4, v4, v10
	s_waitcnt lgkmcnt(4)
	v_add_f32_e32 v5, v5, v11
	s_waitcnt lgkmcnt(3)
	v_add_f32_e32 v6, v6, v12
	s_waitcnt lgkmcnt(2)
	v_add_f32_e32 v7, v7, v13
	s_waitcnt lgkmcnt(1)
	v_add_f32_e32 v8, v8, v14
	s_waitcnt lgkmcnt(0)
	v_add_f32_e32 v10, v9, v15
	ds_bpermute_b32 v2, v44, v0
	ds_bpermute_b32 v3, v44, v1
	ds_bpermute_b32 v9, v44, v4
	ds_bpermute_b32 v11, v44, v5
	ds_bpermute_b32 v12, v44, v6
	ds_bpermute_b32 v13, v44, v7
	ds_bpermute_b32 v14, v44, v8
	ds_bpermute_b32 v15, v44, v10
	s_waitcnt lgkmcnt(6)
	v_pk_add_f32 v[0:1], v[0:1], v[2:3]
	s_waitcnt lgkmcnt(5)
	v_add_f32_e32 v4, v4, v9
	s_waitcnt lgkmcnt(4)
	v_add_f32_e32 v5, v5, v11
	s_waitcnt lgkmcnt(3)
	v_add_f32_e32 v6, v6, v12
	s_waitcnt lgkmcnt(2)
	v_add_f32_e32 v7, v7, v13
	s_waitcnt lgkmcnt(1)
	v_add_f32_e32 v9, v8, v14
	s_waitcnt lgkmcnt(0)
	v_add_f32_e32 v11, v10, v15
	ds_bpermute_b32 v2, v45, v0
	ds_bpermute_b32 v3, v45, v1
	ds_bpermute_b32 v8, v45, v4
	ds_bpermute_b32 v10, v45, v5
	ds_bpermute_b32 v12, v45, v6
	ds_bpermute_b32 v13, v45, v7
	ds_bpermute_b32 v14, v45, v9
	ds_bpermute_b32 v15, v45, v11
	global_store_dword v[38:39], v55, off
	global_store_dword v[38:39], v56, off offset:256
	global_store_dword v[38:39], v57, off offset:512
	global_store_dword v[38:39], v58, off offset:768
	s_and_saveexec_b64 s[34:35], s[4:5]
	s_cbranch_execz .LBB0_1059
	s_waitcnt lgkmcnt(6)
	v_pk_add_f32 v[2:3], v[0:1], v[2:3]
	s_waitcnt lgkmcnt(5)
	v_add_f32_e32 v4, v4, v8
	v_cmp_gt_f32_e32 vcc, v3, v2
	s_waitcnt lgkmcnt(4)
	v_add_f32_e32 v5, v5, v10
	s_waitcnt lgkmcnt(3)
	v_add_f32_e32 v6, v6, v12
	v_cndmask_b32_e32 v0, v2, v3, vcc
	v_cmp_gt_f32_e64 s[6:7], v4, v0
	s_waitcnt lgkmcnt(2)
	v_add_f32_e32 v7, v7, v13
	s_waitcnt lgkmcnt(1)
	v_add_f32_e32 v9, v9, v14
	v_cndmask_b32_e64 v0, v0, v4, s[6:7]
	v_cmp_gt_f32_e64 s[8:9], v5, v0
	s_waitcnt lgkmcnt(0)
	v_add_f32_e32 v11, v11, v15
	v_cmp_lt_f32_e64 s[18:19], s37, v2
	v_cndmask_b32_e64 v0, v0, v5, s[8:9]
	v_cmp_gt_f32_e64 s[10:11], v6, v0
	s_ashr_i32 s21, s20, 31
	s_nop 0
	v_cndmask_b32_e64 v0, v0, v6, s[10:11]
	v_cmp_gt_f32_e64 s[12:13], v7, v0
	s_nop 1
	v_cndmask_b32_e64 v0, v0, v7, s[12:13]
	v_cmp_gt_f32_e64 s[14:15], v9, v0
	s_nop 1
	v_cndmask_b32_e64 v1, v0, v9, s[14:15]
	v_cndmask_b32_e64 v0, 0, 1, vcc
	v_cndmask_b32_e64 v0, v0, 2, s[6:7]
	v_cndmask_b32_e64 v0, v0, 3, s[8:9]
	v_cndmask_b32_e64 v0, v0, 4, s[10:11]
	v_cndmask_b32_e64 v0, v0, 5, s[12:13]
	v_cndmask_b32_e64 v0, v0, 6, s[14:15]
	v_cmp_ngt_f32_e32 vcc, v11, v1
	s_and_b64 s[42:43], s[14:15], vcc
	s_nop 0
	v_cndmask_b32_e32 v0, 7, v0, vcc
	v_cmp_ne_u32_e64 s[16:17], 0, v0
	s_and_b64 s[16:17], s[16:17], s[18:19]
	v_cmp_ne_u32_e64 s[14:15], 1, v0
	v_cndmask_b32_e64 v2, v53, v2, s[16:17]
	v_cmp_gt_f32_e64 s[16:17], v3, v2
	s_and_b64 s[14:15], s[14:15], s[16:17]
	v_cndmask_b32_e64 v2, v2, v3, s[14:15]
	v_cmp_ne_u32_e64 s[12:13], 2, v0
	v_cmp_gt_f32_e64 s[16:17], v4, v2
	s_and_b64 s[12:13], s[12:13], s[16:17]
	v_cndmask_b32_e64 v2, v2, v4, s[12:13]
	v_cmp_ne_u32_e64 s[10:11], 3, v0
	v_cmp_gt_f32_e64 s[16:17], v5, v2
	s_and_b64 s[10:11], s[10:11], s[16:17]
	v_cndmask_b32_e64 v2, v2, v5, s[10:11]
	v_cmp_ne_u32_e64 s[8:9], 4, v0
	v_cmp_gt_f32_e64 s[16:17], v6, v2
	s_and_b64 s[8:9], s[8:9], s[16:17]
	v_cndmask_b32_e64 v2, v2, v6, s[8:9]
	v_cmp_ne_u32_e64 s[6:7], 5, v0
	v_cmp_gt_f32_e64 s[16:17], v7, v2
	s_and_b64 s[6:7], s[6:7], s[16:17]
	v_cndmask_b32_e64 v2, v2, v7, s[6:7]
	v_cmp_ngt_f32_e64 s[16:17], v9, v2
	s_or_b64 s[16:17], s[42:43], s[16:17]
	v_cndmask_b32_e32 v1, v11, v1, vcc
	v_cndmask_b32_e64 v2, v9, v2, s[16:17]
	v_cmp_gt_f32_e64 s[18:19], v11, v2
	s_and_b64 s[18:19], vcc, s[18:19]
	v_cndmask_b32_e64 v3, 0, 1, s[14:15]
	v_cndmask_b32_e64 v2, v2, v11, s[18:19]
	v_sub_f32_e32 v4, v2, v1
	v_mul_f32_e32 v1, 0x3fb8aa3b, v4
	v_fma_f32 v2, v4, s38, -v1
	v_rndne_f32_e32 v5, v1
	v_fmac_f32_e32 v2, 0x32a5705f, v4
	v_sub_f32_e32 v1, v1, v5
	v_add_f32_e32 v1, v1, v2
	v_cndmask_b32_e64 v3, v3, 2, s[12:13]
	v_exp_f32_e32 v1, v1
	v_cvt_i32_f32_e32 v5, v5
	v_cndmask_b32_e64 v3, v3, 3, s[10:11]
	v_cndmask_b32_e64 v3, v3, 4, s[8:9]
	v_cndmask_b32_e64 v2, v3, 5, s[6:7]
	v_cndmask_b32_e64 v2, 6, v2, s[16:17]
	v_ldexp_f32 v1, v1, v5
	v_cmp_ngt_f32_e32 vcc, s39, v4
	v_cndmask_b32_e64 v2, v2, 7, s[18:19]
	v_lshl_add_u32 v3, v2, 2, 0
	v_cndmask_b32_e32 v5, 0, v1, vcc
	v_lshl_add_u32 v1, v0, 2, 0
	ds_add_rtn_u32 v1, v1, v52 offset:32768
	ds_add_rtn_u32 v3, v3, v52 offset:32768
	v_cmp_nlt_f32_e32 vcc, s40, v4
	s_and_b32 s6, s3, 60
	v_lshl_add_u32 v6, s6, 2, v46
	v_cndmask_b32_e32 v4, v54, v5, vcc
	v_add_f32_e32 v5, 1.0, v4
	s_waitcnt lgkmcnt(0)
	ds_write_b128 v6, v[0:3] offset:32832
	v_div_scale_f32 v0, s[6:7], v5, v5, v4
	v_rcp_f32_e32 v1, v0
	s_lshl_b64 s[6:7], s[20:21], 2
	s_add_u32 s6, s54, s6
	s_addc_u32 s7, s55, s7
	v_fma_f32 v2, -v0, v1, 1.0
	v_fmac_f32_e32 v1, v2, v1
	v_div_scale_f32 v2, vcc, v4, v5, v4
	v_mul_f32_e32 v3, v2, v1
	v_fma_f32 v6, -v0, v3, v2
	v_fmac_f32_e32 v3, v6, v1
	v_fma_f32 v0, -v0, v3, v2
	v_div_scale_f32 v2, s[8:9], v5, v5, 1.0
	v_rcp_f32_e32 v6, v2
	v_div_fmas_f32 v0, v0, v1, v3
	v_div_fixup_f32 v1, v0, v5, v4
	v_fma_f32 v0, -v2, v6, 1.0
	v_fmac_f32_e32 v6, v0, v6
	v_div_scale_f32 v0, vcc, 1.0, v5, 1.0
	v_mul_f32_e32 v3, v0, v6
	v_fma_f32 v4, -v2, v3, v0
	v_fmac_f32_e32 v3, v4, v6
	v_fma_f32 v0, -v2, v3, v0
	v_div_fmas_f32 v0, v0, v6, v3
	v_div_fixup_f32 v0, v0, v5, 1.0
	global_store_dwordx2 v47, v[0:1], s[6:7]
	s_branch .LBB0_1059

.LBB0_1411:
	s_ashr_i32 s3, s2, 31
	v_lshl_add_u64 v[8:9], s[8:9], 0, v[2:3]
	s_lshl_b64 s[0:1], s[2:3], 2
	v_add_co_u32_e32 v8, vcc, s12, v8
	s_add_u32 s14, s50, s0
	s_nop 0
	v_addc_co_u32_e32 v9, vcc, 0, v9, vcc
	s_addc_u32 s15, s51, s1
	global_load_dwordx4 v[22:25], v[4:5], off
	global_load_dwordx4 v[26:29], v[6:7], off
	global_load_dwordx4 v[30:33], v[8:9], off nt
	global_load_dwordx4 v[34:37], v[8:9], off offset:1024 nt
	global_load_dwordx4 v[38:41], v[8:9], off offset:2048 nt
	global_load_dwordx4 v[42:45], v[8:9], off offset:3072 nt
	s_add_u32 s0, s54, s0
	global_load_dwordx2 v[8:9], v18, s[14:15]
	s_addc_u32 s1, s55, s1
	global_load_dwordx2 v[46:47], v18, s[0:1]
	v_lshl_add_u64 v[10:11], s[4:5], 0, v[2:3]
	s_add_i32 s46, s46, s80
	s_add_i32 s2, s2, s11
	s_add_u32 s4, s4, s6
	s_addc_u32 s5, s5, s7
	s_add_u32 s8, s8, s6
	s_addc_u32 s9, s9, s7
	s_cmpk_lt_i32 s46, 0x4000
	s_waitcnt vmcnt(1)
	v_ashrrev_i32_e32 v49, 31, v8
	v_mov_b32_e32 v48, v8
	v_ashrrev_i32_e32 v51, 31, v9
	v_mov_b32_e32 v50, v9
	v_lshlrev_b64 v[8:9], 11, v[48:49]
	v_lshlrev_b64 v[48:49], 11, v[50:51]
	v_lshl_add_u64 v[8:9], v[0:1], 0, v[8:9]
	v_lshl_add_u64 v[48:49], v[0:1], 0, v[48:49]
	global_load_dwordx2 v[50:51], v[8:9], off nt
	global_load_dwordx2 v[52:53], v[48:49], off nt
	global_load_dwordx2 v[54:55], v[8:9], off offset:512 nt
	global_load_dwordx2 v[56:57], v[48:49], off offset:512 nt
	global_load_dwordx2 v[58:59], v[8:9], off offset:1024 nt
	global_load_dwordx2 v[60:61], v[48:49], off offset:1024 nt
	global_load_dwordx2 v[62:63], v[8:9], off offset:1536 nt
	global_load_dwordx2 v[64:65], v[48:49], off offset:1536 nt
	s_waitcnt vmcnt(7)
	v_lshlrev_b32_e32 v8, 16, v50
	v_and_b32_e32 v9, 0xffff0000, v50
	v_lshlrev_b32_e32 v48, 16, v51
	v_and_b32_e32 v49, 0xffff0000, v51
	s_waitcnt vmcnt(6)
	v_lshlrev_b32_e32 v50, 16, v52
	v_and_b32_e32 v51, 0xffff0000, v52
	v_lshlrev_b32_e32 v52, 16, v53
	v_and_b32_e32 v53, 0xffff0000, v53
	s_waitcnt vmcnt(4)
	v_lshlrev_b32_e32 v68, 16, v56
	v_and_b32_e32 v69, 0xffff0000, v56
	v_lshlrev_b32_e32 v56, 16, v57
	v_and_b32_e32 v57, 0xffff0000, v57
	v_lshlrev_b32_e32 v66, 16, v54
	v_and_b32_e32 v67, 0xffff0000, v54
	v_lshlrev_b32_e32 v54, 16, v55
	v_and_b32_e32 v55, 0xffff0000, v55
	s_waitcnt vmcnt(2)
	v_lshlrev_b32_e32 v72, 16, v60
	v_and_b32_e32 v73, 0xffff0000, v60
	v_lshlrev_b32_e32 v60, 16, v61
	v_and_b32_e32 v61, 0xffff0000, v61
	s_waitcnt vmcnt(0)
	v_lshlrev_b32_e32 v76, 16, v64
	v_and_b32_e32 v77, 0xffff0000, v64
	v_lshlrev_b32_e32 v64, 16, v65
	v_and_b32_e32 v65, 0xffff0000, v65
	v_pk_mul_f32 v[52:53], v[46:47], v[52:53] op_sel:[1,0]
	v_pk_mul_f32 v[50:51], v[46:47], v[50:51] op_sel:[1,0]
	v_pk_mul_f32 v[56:57], v[46:47], v[56:57] op_sel:[1,0]
	v_pk_mul_f32 v[68:69], v[46:47], v[68:69] op_sel:[1,0]
	v_lshlrev_b32_e32 v70, 16, v58
	v_and_b32_e32 v71, 0xffff0000, v58
	v_lshlrev_b32_e32 v58, 16, v59
	v_and_b32_e32 v59, 0xffff0000, v59
	v_lshlrev_b32_e32 v74, 16, v62
	v_and_b32_e32 v75, 0xffff0000, v62
	v_lshlrev_b32_e32 v62, 16, v63
	v_and_b32_e32 v63, 0xffff0000, v63
	v_pk_mul_f32 v[60:61], v[46:47], v[60:61] op_sel:[1,0]
	v_pk_mul_f32 v[72:73], v[46:47], v[72:73] op_sel:[1,0]
	v_pk_mul_f32 v[64:65], v[46:47], v[64:65] op_sel:[1,0]
	v_pk_mul_f32 v[76:77], v[46:47], v[76:77] op_sel:[1,0]
	v_pk_fma_f32 v[8:9], v[46:47], v[8:9], v[50:51] op_sel_hi:[0,1,1]
	v_pk_fma_f32 v[48:49], v[46:47], v[48:49], v[52:53] op_sel_hi:[0,1,1]
	v_pk_fma_f32 v[50:51], v[46:47], v[66:67], v[68:69] op_sel_hi:[0,1,1]
	v_pk_fma_f32 v[52:53], v[46:47], v[54:55], v[56:57] op_sel_hi:[0,1,1]
	v_pk_fma_f32 v[54:55], v[46:47], v[70:71], v[72:73] op_sel_hi:[0,1,1]
	v_pk_fma_f32 v[56:57], v[46:47], v[58:59], v[60:61] op_sel_hi:[0,1,1]
	v_pk_fma_f32 v[58:59], v[46:47], v[74:75], v[76:77] op_sel_hi:[0,1,1]
	v_pk_fma_f32 v[46:47], v[46:47], v[62:63], v[64:65] op_sel_hi:[0,1,1]
	v_pk_fma_f32 v[32:33], v[32:33], s[10:11], v[48:49] op_sel_hi:[1,0,1]
	v_pk_fma_f32 v[8:9], v[30:31], s[10:11], v[8:9] op_sel_hi:[1,0,1]
	v_pk_fma_f32 v[30:31], v[36:37], s[10:11], v[52:53] op_sel_hi:[1,0,1]
	v_pk_fma_f32 v[34:35], v[34:35], s[10:11], v[50:51] op_sel_hi:[1,0,1]
	v_pk_fma_f32 v[36:37], v[40:41], s[10:11], v[56:57] op_sel_hi:[1,0,1]
	v_pk_fma_f32 v[40:41], v[44:45], s[10:11], v[46:47] op_sel_hi:[1,0,1]
	v_pk_mov_b32 v[44:45], v[8:9], v[32:33] op_sel:[1,0]
	v_mov_b32_e32 v46, v8
	v_mov_b32_e32 v47, v33
	v_pk_mov_b32 v[48:49], v[34:35], v[30:31] op_sel:[1,0]
	v_mov_b32_e32 v50, v34
	v_mov_b32_e32 v51, v31
	v_pk_add_f32 v[44:45], v[44:45], v[46:47]
	v_pk_add_f32 v[46:47], v[48:49], v[50:51]
	v_pk_fma_f32 v[38:39], v[38:39], s[10:11], v[54:55] op_sel_hi:[1,0,1]
	v_pk_fma_f32 v[42:43], v[42:43], s[10:11], v[58:59] op_sel_hi:[1,0,1]
	v_add_f32_e32 v21, v44, v45
	v_pk_add_f32 v[44:45], v[46:47], v[46:47] op_sel:[0,1] op_sel_hi:[1,0]
	v_add_f32_e32 v52, v38, v39
	v_add_f32_e32 v54, v36, v37
	v_mov_b32_e32 v57, v42
	v_mov_b32_e32 v53, v40
	v_mov_b32_e32 v55, v41
	v_add_f32_e32 v56, 0, v21
	v_mov_b32_e32 v45, v43
	v_pk_add_f32 v[48:49], v[52:53], v[54:55]
	v_pk_add_f32 v[44:45], v[56:57], v[44:45]
	s_nop 0
	v_pk_add_f32 v[44:45], v[44:45], v[48:49]
	s_nop 0
	v_add_f32_e32 v21, v44, v45
	ds_bpermute_b32 v44, v12, v21
	s_waitcnt lgkmcnt(0)
	v_add_f32_e32 v21, v21, v44
	ds_bpermute_b32 v44, v13, v21
	s_waitcnt lgkmcnt(0)
	v_add_f32_e32 v21, v21, v44
	ds_bpermute_b32 v44, v14, v21
	s_waitcnt lgkmcnt(0)
	v_add_f32_e32 v21, v21, v44
	ds_bpermute_b32 v44, v15, v21
	s_waitcnt lgkmcnt(0)
	v_add_f32_e32 v21, v21, v44
	ds_bpermute_b32 v44, v16, v21
	s_waitcnt lgkmcnt(0)
	v_add_f32_e32 v21, v21, v44
	ds_bpermute_b32 v44, v17, v21
	s_waitcnt lgkmcnt(0)
	v_add_f32_e32 v21, v21, v44
	v_fmamk_f32 v9, v21, 0xba800000, v9
	v_fmac_f32_e32 v8, 0xba800000, v21
	v_fmamk_f32 v33, v21, 0xba800000, v33
	v_fmac_f32_e32 v32, 0xba800000, v21
	v_fmamk_f32 v35, v21, 0xba800000, v35
	v_fmac_f32_e32 v34, 0xba800000, v21
	v_fmamk_f32 v31, v21, 0xba800000, v31
	v_fmac_f32_e32 v30, 0xba800000, v21
	v_pk_mul_f32 v[44:45], v[32:33], v[32:33]
	v_pk_mul_f32 v[46:47], v[8:9], v[8:9]
	v_pk_mul_f32 v[48:49], v[30:31], v[30:31]
	v_pk_mul_f32 v[50:51], v[34:35], v[34:35]
	v_fmac_f32_e32 v38, 0xba800000, v21
	v_fmac_f32_e32 v36, 0xba800000, v21
	v_pk_mov_b32 v[56:57], v[46:47], v[44:45] op_sel:[1,0]
	v_mov_b32_e32 v47, v45
	v_pk_mov_b32 v[44:45], v[50:51], v[48:49] op_sel:[1,0]
	v_mov_b32_e32 v51, v49
	v_fmamk_f32 v39, v21, 0xba800000, v39
	v_fmamk_f32 v37, v21, 0xba800000, v37
	v_mul_f32_e32 v52, v38, v38
	v_mul_f32_e32 v54, v36, v36
	v_pk_add_f32 v[46:47], v[56:57], v[46:47]
	v_pk_add_f32 v[44:45], v[44:45], v[50:51]
	v_fmamk_f32 v41, v21, 0xba800000, v41
	v_fmac_f32_e32 v40, 0xba800000, v21
	v_fmamk_f32 v43, v21, 0xba800000, v43
	v_fmac_f32_e32 v42, 0xba800000, v21
	v_pk_fma_f32 v[48:49], v[38:39], v[38:39], v[52:53] op_sel_hi:[1,1,0]
	v_pk_fma_f32 v[52:53], v[36:37], v[36:37], v[54:55] op_sel_hi:[1,1,0]
	v_pk_add_f32 v[46:47], v[46:47], v[46:47] op_sel_hi:[0,1]
	v_pk_add_f32 v[44:45], v[44:45], v[44:45] op_sel_hi:[0,1]
	v_mul_f32_e32 v48, v42, v42
	v_mul_f32_e32 v52, v43, v43
	v_mul_f32_e32 v46, v40, v40
	v_mul_f32_e32 v44, v41, v41
	v_pk_add_f32 v[48:49], v[48:49], v[52:53]
	v_pk_add_f32 v[44:45], v[46:47], v[44:45]
	s_nop 0
	v_pk_add_f32 v[44:45], v[48:49], v[44:45]
	s_nop 0
	v_add_f32_e32 v21, v44, v45
	ds_bpermute_b32 v44, v12, v21
	s_waitcnt lgkmcnt(0)
	v_add_f32_e32 v21, v21, v44
	ds_bpermute_b32 v44, v13, v21
	s_waitcnt lgkmcnt(0)
	v_add_f32_e32 v21, v21, v44
	ds_bpermute_b32 v44, v14, v21
	s_waitcnt lgkmcnt(0)
	v_add_f32_e32 v21, v21, v44
	ds_bpermute_b32 v44, v15, v21
	s_waitcnt lgkmcnt(0)
	v_add_f32_e32 v21, v21, v44
	ds_bpermute_b32 v44, v16, v21
	s_waitcnt lgkmcnt(0)
	v_add_f32_e32 v21, v21, v44
	ds_bpermute_b32 v44, v17, v21
	s_waitcnt lgkmcnt(0)
	v_add_f32_e32 v21, v21, v44
	v_fmamk_f32 v21, v21, 0x3a800000, v19
	v_mul_f32_e32 v44, 0x4f800000, v21
	v_cmp_gt_f32_e32 vcc, s13, v21
	s_nop 1
	v_cndmask_b32_e32 v21, v21, v44, vcc
	v_sqrt_f32_e32 v44, v21
	s_nop 0
	v_add_u32_e32 v45, -1, v44
	v_add_u32_e32 v46, 1, v44
	v_fma_f32 v47, -v45, v44, v21
	v_fma_f32 v48, -v46, v44, v21
	v_cmp_ge_f32_e64 s[0:1], 0, v47
	s_nop 1
	v_cndmask_b32_e64 v44, v44, v45, s[0:1]
	v_cmp_lt_f32_e64 s[0:1], 0, v48
	s_nop 1
	v_cndmask_b32_e64 v44, v44, v46, s[0:1]
	v_mul_f32_e32 v45, 0x37800000, v44
	v_cndmask_b32_e32 v44, v44, v45, vcc
	v_cmp_class_f32_e32 vcc, v21, v20
	s_nop 1
	v_cndmask_b32_e32 v21, v44, v21, vcc
	v_div_scale_f32 v44, s[0:1], v21, v21, 1.0
	v_rcp_f32_e32 v46, v44
	v_div_scale_f32 v45, vcc, 1.0, v21, 1.0
	v_fma_f32 v47, -v44, v46, 1.0
	v_fmac_f32_e32 v46, v47, v46
	v_mul_f32_e32 v47, v45, v46
	v_fma_f32 v48, -v44, v47, v45
	v_fmac_f32_e32 v47, v48, v46
	v_fma_f32 v44, -v44, v47, v45
	v_div_fmas_f32 v44, v44, v46, v47
	v_div_fixup_f32 v44, v44, v21, 1.0
	v_pk_mul_f32 v[8:9], v[8:9], v[44:45] op_sel_hi:[1,0]
	v_pk_mul_f32 v[32:33], v[32:33], v[44:45] op_sel_hi:[1,0]
	v_pk_fma_f32 v[22:23], v[22:23], v[8:9], v[26:27]
	v_pk_fma_f32 v[24:25], v[24:25], v[32:33], v[28:29]
	global_store_dwordx4 v[10:11], v[22:25], off nt
	global_load_dwordx4 v[22:25], v[4:5], off offset:1024
	s_nop 0
	global_load_dwordx4 v[26:29], v[6:7], off offset:1024
	v_pk_mul_f32 v[8:9], v[30:31], v[44:45] op_sel_hi:[1,0]
	v_pk_mul_f32 v[30:31], v[34:35], v[44:45] op_sel_hi:[1,0]
	s_waitcnt vmcnt(0)
	v_pk_fma_f32 v[24:25], v[24:25], v[8:9], v[28:29]
	v_pk_fma_f32 v[22:23], v[22:23], v[30:31], v[26:27]
	global_store_dwordx4 v[10:11], v[22:25], off offset:1024 nt
	global_load_dwordx4 v[22:25], v[4:5], off offset:2048
	s_nop 0
	global_load_dwordx4 v[26:29], v[6:7], off offset:2048
	v_pk_mul_f32 v[8:9], v[36:37], v[44:45] op_sel_hi:[1,0]
	v_pk_mul_f32 v[30:31], v[38:39], v[44:45] op_sel_hi:[1,0]
	s_waitcnt vmcnt(0)
	v_pk_fma_f32 v[24:25], v[24:25], v[8:9], v[28:29]
	v_pk_fma_f32 v[22:23], v[22:23], v[30:31], v[26:27]
	global_store_dwordx4 v[10:11], v[22:25], off offset:2048 nt
	global_load_dwordx4 v[22:25], v[4:5], off offset:3072
	s_nop 0
	global_load_dwordx4 v[26:29], v[6:7], off offset:3072
	v_pk_mul_f32 v[8:9], v[40:41], v[44:45] op_sel_hi:[1,0]
	v_pk_mul_f32 v[30:31], v[42:43], v[44:45] op_sel_hi:[1,0]
	s_waitcnt vmcnt(0)
	v_pk_fma_f32 v[24:25], v[24:25], v[8:9], v[28:29]
	v_pk_fma_f32 v[22:23], v[22:23], v[30:31], v[26:27]
	global_store_dwordx4 v[10:11], v[22:25], off offset:3072 nt
	s_cbranch_scc1 .LBB0_1411
